# top-k rounds: rotate 3 compare masks (vcc + 2 SGPR pairs) and fuse DPP max to drop ~40 hazard nops/slots per round (on top of permlane merge)
# speedup vs baseline: 1.0005x; 1.0005x over previous
; template <int CTRL> DI float dpp_f(float x) { return __builtin_bit_cast(float, __builtin_amdgcn_update_dpp(0, __builtin_bit_cast(int, x), CTRL, 0xF, 0xF, true)); }
; template <int CTRL> DI int dpp_i(int x) { return __builtin_amdgcn_update_dpp(0, x, CTRL, 0xF, 0xF, true); }
; template <int DV>
; DI void attn_unit(const int wv, const Args& A, LAS unsigned char* lds, int b, int g, int qb, int dry) {
;     ...
;             for (int round = 0; round < 13; ++round) {
;                 float lm = sc[0];
; #pragma unroll
;                 for (int i = 1; i < 16; ++i) lm = fmaxf(lm, sc[i]);
;                 lm = fmaxf(lm, dpp_f<0xB1>(lm)); lm = fmaxf(lm, dpp_f<0x4E>(lm)); lm = fmaxf(lm, dpp_f<0x141>(lm));
;                 int li = 99;
; #pragma unroll
;                 for (int i = 15; i >= 0; --i) li = (sc[i] == lm) ? i : li;
;                 int cj = (li < 16) ? (l8 + 8 * li) : 999;
;                 cj = min(cj, dpp_i<0xB1>(cj)); cj = min(cj, dpp_i<0x4E>(cj)); cj = min(cj, dpp_i<0x141>(cj));
;                 const int tt = cj - l8;
; #pragma unroll
;                 for (int i = 0; i < 16; ++i) { const bool hit = (tt == 8 * i); sc[i] = hit ? -1.f : sc[i]; selm |= hit ? (1u << i) : 0u; }
;             }
.LBB0_868:
	s_waitcnt lgkmcnt(0)
	v_max_f32_e32 v58, v0, v0
	v_max_f32_e32 v60, v1, v1
	v_max_f32_e32 v58, v60, v58
	v_max3_f32 v58, v58, v41, v39
	v_max3_f32 v58, v58, v46, v45
	v_max3_f32 v58, v58, v49, v48
	v_max3_f32 v58, v58, v51, v50
	v_max3_f32 v58, v58, v53, v52
	v_max3_f32 v58, v58, v55, v54
	v_max3_f32 v58, v58, v57, v56
	s_add_i32 s8, s8, -1
	s_cmp_eq_u32 s8, 0
	v_max_f32_dpp v58, v58, v58 quad_perm:[1,0,3,2] row_mask:0xf bank_mask:0xf bound_ctrl:1
	s_nop 1
	v_max_f32_dpp v58, v58, v58 quad_perm:[2,3,0,1] row_mask:0xf bank_mask:0xf bound_ctrl:1
	s_nop 1
	v_max_f32_dpp v58, v58, v58 row_half_mirror row_mask:0xf bank_mask:0xf bound_ctrl:1
	v_cmp_eq_f32_e32 vcc, v56, v58
	v_cmp_neq_f32_e64 s[100:101], v57, v58
	v_cmp_neq_f32_e64 s[98:99], v54, v58
	v_cndmask_b32_e64 v60, v205, 15, vcc
	v_cmp_neq_f32_e32 vcc, v55, v58
	v_cndmask_b32_e64 v60, 14, v60, s[100:101]
	v_cmp_neq_f32_e64 s[100:101], v52, v58
	v_cndmask_b32_e64 v60, 13, v60, s[98:99]
	v_cmp_neq_f32_e64 s[98:99], v53, v58
	v_cndmask_b32_e64 v60, 12, v60, vcc
	v_cmp_neq_f32_e32 vcc, v50, v58
	v_cndmask_b32_e64 v60, 11, v60, s[100:101]
	v_cmp_neq_f32_e64 s[100:101], v51, v58
	v_cndmask_b32_e64 v60, 10, v60, s[98:99]
	v_cmp_neq_f32_e64 s[98:99], v48, v58
	v_cndmask_b32_e64 v60, 9, v60, vcc
	v_cmp_neq_f32_e32 vcc, v49, v58
	v_cndmask_b32_e64 v60, 8, v60, s[100:101]
	v_cmp_neq_f32_e64 s[100:101], v45, v58
	v_cndmask_b32_e64 v60, 7, v60, s[98:99]
	v_cmp_neq_f32_e64 s[98:99], v46, v58
	v_cndmask_b32_e64 v60, 6, v60, vcc
	v_cmp_neq_f32_e32 vcc, v39, v58
	v_cndmask_b32_e64 v60, 5, v60, s[100:101]
	v_cmp_neq_f32_e64 s[100:101], v41, v58
	v_cndmask_b32_e64 v60, 4, v60, s[98:99]
	v_cmp_neq_f32_e64 s[98:99], v0, v58
	v_cndmask_b32_e64 v60, 3, v60, vcc
	v_cmp_neq_f32_e32 vcc, v1, v58
	v_cndmask_b32_e64 v60, 2, v60, s[100:101]
	v_cndmask_b32_e64 v60, 1, v60, s[98:99]
	v_cndmask_b32_e64 v58, 0, v60, vcc
	v_cmp_gt_u32_e32 vcc, 16, v58
	v_lshl_or_b32 v58, v58, 3, v40
	s_nop 0
	v_cndmask_b32_e32 v58, v206, v58, vcc
	s_nop 1
	v_min_i32_dpp v58, v58, v58 quad_perm:[1,0,3,2] row_mask:0xf bank_mask:0xf bound_ctrl:1
	s_nop 1
	v_min_i32_dpp v58, v58, v58 quad_perm:[2,3,0,1] row_mask:0xf bank_mask:0xf bound_ctrl:1
	s_nop 1
	v_min_i32_dpp v58, v58, v58 row_half_mirror row_mask:0xf bank_mask:0xf bound_ctrl:1
	v_sub_u32_e32 v67, v58, v40
	v_cmp_eq_u32_e32 vcc, v58, v40
	v_cmp_eq_u32_e64 s[98:99], 8, v67
	v_cmp_eq_u32_e64 s[100:101], 16, v67
	v_cndmask_b32_e64 v58, 0, 1, vcc
	v_cndmask_b32_e64 v1, v1, -1.0, vcc
	v_or_b32_e32 v63, v59, v58
	v_cmp_eq_u32_e32 vcc, 24, v67
	v_cndmask_b32_e64 v58, 0, 2, s[98:99]
	v_cndmask_b32_e64 v0, v0, -1.0, s[98:99]
	v_or_b32_e32 v62, v58, v63
	v_cmp_eq_u32_e64 s[98:99], 32, v67
	v_cndmask_b32_e64 v58, 0, 4, s[100:101]
	v_cndmask_b32_e64 v41, v41, -1.0, s[100:101]
	v_cmp_eq_u32_e64 s[100:101], 40, v67
	v_cndmask_b32_e64 v59, 0, 8, vcc
	v_cndmask_b32_e64 v39, v39, -1.0, vcc
	v_or3_b32 v61, v58, v59, v62
	v_cmp_eq_u32_e32 vcc, 48, v67
	v_cndmask_b32_e64 v58, 0, 16, s[98:99]
	v_cndmask_b32_e64 v46, v46, -1.0, s[98:99]
	v_cmp_eq_u32_e64 s[98:99], 56, v67
	v_cndmask_b32_e64 v59, 0, 32, s[100:101]
	v_cndmask_b32_e64 v45, v45, -1.0, s[100:101]
	v_or3_b32 v60, v58, v59, v61
	v_cmp_eq_u32_e64 s[100:101], 64, v67
	v_cndmask_b32_e64 v58, 0, 64, vcc
	v_cndmask_b32_e64 v49, v49, -1.0, vcc
	v_cmp_eq_u32_e32 vcc, 0x48, v67
	v_cndmask_b32_e64 v59, 0, v192, s[98:99]
	v_cndmask_b32_e64 v48, v48, -1.0, s[98:99]
	v_or3_b32 v58, v58, v59, v60
	s_movk_i32 s9, 0x50
	v_cmp_eq_u32_e64 s[98:99], s9, v67
	v_cndmask_b32_e64 v59, 0, v193, s[100:101]
	v_cndmask_b32_e64 v51, v51, -1.0, s[100:101]
	s_movk_i32 s9, 0x58
	v_cmp_eq_u32_e64 s[100:101], s9, v67
	v_cndmask_b32_e64 v64, 0, v194, vcc
	v_cndmask_b32_e64 v50, v50, -1.0, vcc
	v_or3_b32 v64, v59, v64, v58
	v_cmp_eq_u32_e32 vcc, 0x60, v67
	v_cndmask_b32_e64 v59, 0, v195, s[98:99]
	v_cndmask_b32_e64 v53, v53, -1.0, s[98:99]
	s_movk_i32 s9, 0x68
	v_cmp_eq_u32_e64 s[98:99], s9, v67
	v_cndmask_b32_e64 v65, 0, v196, s[100:101]
	v_cndmask_b32_e64 v52, v52, -1.0, s[100:101]
	v_or3_b32 v65, v59, v65, v64
	s_movk_i32 s9, 0x70
	v_cmp_eq_u32_e64 s[100:101], s9, v67
	v_cndmask_b32_e64 v59, 0, v197, vcc
	v_cndmask_b32_e64 v55, v55, -1.0, vcc
	v_cmp_eq_u32_e32 vcc, 0x78, v67
	v_cndmask_b32_e64 v66, 0, v198, s[98:99]
	v_cndmask_b32_e64 v54, v54, -1.0, s[98:99]
	v_or3_b32 v66, v59, v66, v65
	v_cndmask_b32_e64 v59, 0, v199, s[100:101]
	v_cndmask_b32_e64 v57, v57, -1.0, s[100:101]
	v_cndmask_b32_e64 v67, 0, v200, vcc
	v_cndmask_b32_e64 v56, v56, -1.0, vcc
	v_or3_b32 v59, v59, v67, v66
	s_cbranch_scc0 .LBB0_868
; template <int DV>
; DI void attn_unit(const int wv, const Args& A, LAS unsigned char* lds, int b, int g, int qb, int dry) {
;     ...
;             for (int i = 0; i < 16; ++i) { if ((selm >> i) & 1u) { if (i < 8) slo |= 1ull << (l8 + 8 * i); else shi |= 1ull << (l8 + 8 * (i - 8)); } }
	v_and_b32_e32 v0, 1, v63
	v_lshlrev_b64 v[48:49], v40, 1
	v_cmp_eq_u32_e32 vcc, 1, v0
	v_lshlrev_b64 v[50:51], v36, 1
	v_and_b32_e32 v36, 2, v62
	v_cndmask_b32_e32 v0, 0, v49, vcc
	v_cndmask_b32_e32 v1, 0, v48, vcc
	v_cmp_ne_u32_e32 vcc, 0, v36
	v_and_b32_e32 v46, 8, v61
	v_and_b32_e32 v55, 0x80, v58
	v_cndmask_b32_e32 v39, 0, v50, vcc
	v_cndmask_b32_e32 v36, 0, v51, vcc
	v_or_b32_e32 v1, v39, v1
	v_and_b32_e32 v39, 4, v61
	v_or_b32_e32 v0, v36, v0
	v_lshlrev_b64 v[36:37], v37, 1
	v_cmp_ne_u32_e32 vcc, 0, v39
	v_lshlrev_b64 v[38:39], v38, 1
	s_mov_b64 s[8:9], 0
	v_cndmask_b32_e32 v41, 0, v37, vcc
	v_cndmask_b32_e32 v45, 0, v36, vcc
	v_cmp_ne_u32_e32 vcc, 0, v46
	s_nop 1
	v_cndmask_b32_e32 v46, 0, v39, vcc
	v_cndmask_b32_e32 v52, 0, v38, vcc
	v_or3_b32 v0, v0, v41, v46
	v_and_b32_e32 v41, 16, v60
	v_or3_b32 v1, v1, v45, v52
	v_lshlrev_b64 v[52:53], v42, 1
	v_cmp_ne_u32_e32 vcc, 0, v41
	v_and_b32_e32 v46, 32, v60
	v_lshlrev_b64 v[42:43], v43, 1
	v_cndmask_b32_e32 v41, 0, v53, vcc
	v_cndmask_b32_e32 v45, 0, v52, vcc
	v_cmp_ne_u32_e32 vcc, 0, v46
	s_nop 1
	v_cndmask_b32_e32 v46, 0, v43, vcc
	v_cndmask_b32_e32 v54, 0, v42, vcc
	v_or3_b32 v0, v0, v41, v46
	v_or3_b32 v41, v1, v45, v54
	v_and_b32_e32 v1, 64, v58
	v_lshlrev_b64 v[44:45], v44, 1
	v_cmp_ne_u32_e32 vcc, 0, v1
	v_lshlrev_b64 v[46:47], v47, 1
	s_nop 0
	v_cndmask_b32_e32 v1, 0, v45, vcc
	v_cndmask_b32_e32 v54, 0, v44, vcc
	v_cmp_ne_u32_e32 vcc, 0, v55
	s_nop 1
	v_cndmask_b32_e32 v55, 0, v47, vcc
	v_cndmask_b32_e32 v56, 0, v46, vcc
	v_or3_b32 v1, v0, v1, v55
	v_or3_b32 v0, v41, v54, v56
	v_and_b32_e32 v41, 0x100, v64
	v_cmp_ne_u32_e32 vcc, 0, v41
	s_nop 1
	v_cndmask_b32_e32 v41, 0, v49, vcc
	v_and_b32_e32 v49, 0x200, v64
	v_cndmask_b32_e32 v48, 0, v48, vcc
	v_cmp_ne_u32_e32 vcc, 0, v49
	s_nop 1
	v_cndmask_b32_e32 v49, 0, v51, vcc
	v_or_b32_e32 v41, v41, v49
	v_and_b32_e32 v49, 0x400, v65
	v_cndmask_b32_e32 v50, 0, v50, vcc
	v_cmp_ne_u32_e32 vcc, 0, v49
	v_and_b32_e32 v49, 0x800, v65
	v_or_b32_e32 v48, v48, v50
	v_cndmask_b32_e32 v37, 0, v37, vcc
	v_cndmask_b32_e32 v36, 0, v36, vcc
	v_cmp_ne_u32_e32 vcc, 0, v49
	s_nop 1
	v_cndmask_b32_e32 v38, 0, v38, vcc
	v_cndmask_b32_e32 v39, 0, v39, vcc
	v_or3_b32 v36, v48, v36, v38
	v_and_b32_e32 v38, 0x1000, v66
	v_or3_b32 v37, v41, v37, v39
	v_cmp_ne_u32_e32 vcc, 0, v38
	v_and_b32_e32 v41, 0x2000, v66
	s_nop 0
	v_cndmask_b32_e32 v38, 0, v53, vcc
	v_cndmask_b32_e32 v39, 0, v52, vcc
	v_cmp_ne_u32_e32 vcc, 0, v41
	s_nop 1
	v_cndmask_b32_e32 v41, 0, v43, vcc
	v_or3_b32 v37, v37, v38, v41
	v_and_b32_e32 v38, 0x4000, v59
	v_cndmask_b32_e32 v42, 0, v42, vcc
	v_cmp_ne_u32_e32 vcc, 0, v38
	v_and_b32_e32 v41, 0x8000, v59
	v_or3_b32 v36, v36, v39, v42
	v_cndmask_b32_e32 v38, 0, v45, vcc
	v_cndmask_b32_e32 v39, 0, v44, vcc
	v_cmp_ne_u32_e32 vcc, 0, v41
	s_nop 1
	v_cndmask_b32_e32 v41, 0, v47, vcc
	v_cndmask_b32_e32 v42, 0, v46, vcc
	v_or3_b32 v37, v37, v38, v41
	v_or3_b32 v36, v36, v39, v42
